# nosleep on v111: the sleeps between polls in the split-K hand-off, z-release and final-norm exchange spin loops removed (grid-barrier spins keep theirs)
# speedup vs baseline: 1.0017x; 1.0010x over previous
.LBB0_400:
	global_load_dword v130, v191, s[48:49] sc1
	s_mov_b64 s[50:51], -1
	s_waitcnt vmcnt(0)
	v_cmp_lt_u32_e32 vcc, 7, v130
	s_cbranch_vccnz .LBB0_399
	s_nop 0
	global_load_dword v130, v191, s[48:49] sc1
	s_waitcnt vmcnt(0)
	v_cmp_gt_u32_e32 vcc, 8, v130
	s_cbranch_vccz .LBB0_399
	s_nop 0
	global_load_dword v130, v191, s[48:49] sc1
	s_waitcnt vmcnt(0)
	v_cmp_gt_u32_e32 vcc, 8, v130
	s_cbranch_vccz .LBB0_399
	s_nop 0
	global_load_dword v130, v191, s[48:49] sc1
	s_waitcnt vmcnt(0)
	v_cmp_gt_u32_e32 vcc, 8, v130
	s_cbranch_vccz .LBB0_399
	s_nop 0
	global_load_dword v130, v191, s[48:49] sc1
	s_waitcnt vmcnt(0)
	v_cmp_gt_u32_e32 vcc, 8, v130
	s_cbranch_vccz .LBB0_399
	s_add_i32 s2, s2, -5
	s_cmp_eq_u32 s2, 0
	s_cselect_b64 s[50:51], -1, 0
	s_nop 0
	s_branch .LBB0_399

.LBB0_809:
	s_waitcnt lgkmcnt(0)
	global_load_dword v3, v2, s[84:85] sc1
	s_mov_b64 s[10:11], -1
	s_waitcnt vmcnt(0)
	v_cmp_le_u32_e32 vcc, s3, v3
	s_cbranch_vccnz .LBB0_808
	s_nop 0
	global_load_dword v3, v2, s[84:85] sc1
	s_waitcnt vmcnt(0)
	v_cmp_gt_u32_e32 vcc, s3, v3
	s_cbranch_vccz .LBB0_808
	s_nop 0
	global_load_dword v3, v2, s[84:85] sc1
	s_waitcnt vmcnt(0)
	v_cmp_gt_u32_e32 vcc, s3, v3
	s_cbranch_vccz .LBB0_808
	s_nop 0
	global_load_dword v3, v2, s[84:85] sc1
	s_waitcnt vmcnt(0)
	v_cmp_gt_u32_e32 vcc, s3, v3
	s_cbranch_vccz .LBB0_808
	s_nop 0
	global_load_dword v3, v2, s[84:85] sc1
	s_waitcnt vmcnt(0)
	v_cmp_gt_u32_e32 vcc, s3, v3
	s_cbranch_vccz .LBB0_808
	s_add_i32 s24, s24, -5
	s_cmp_eq_u32 s24, 0
	s_cselect_b64 s[10:11], -1, 0
	s_nop 0
	s_branch .LBB0_808

.LBB0_986:
	global_load_dword v130, v137, s[50:51] sc1
	s_mov_b64 s[66:67], -1
	s_waitcnt vmcnt(0)
	v_cmp_lt_u32_e32 vcc, 7, v130
	s_cbranch_vccnz .LBB0_985
	s_nop 0
	global_load_dword v130, v137, s[50:51] sc1
	s_waitcnt vmcnt(0)
	v_cmp_gt_u32_e32 vcc, 8, v130
	s_cbranch_vccz .LBB0_985
	s_nop 0
	global_load_dword v130, v137, s[50:51] sc1
	s_waitcnt vmcnt(0)
	v_cmp_gt_u32_e32 vcc, 8, v130
	s_cbranch_vccz .LBB0_985
	s_nop 0
	global_load_dword v130, v137, s[50:51] sc1
	s_waitcnt vmcnt(0)
	v_cmp_gt_u32_e32 vcc, 8, v130
	s_cbranch_vccz .LBB0_985
	s_nop 0
	global_load_dword v130, v137, s[50:51] sc1
	s_waitcnt vmcnt(0)
	v_cmp_gt_u32_e32 vcc, 8, v130
	s_cbranch_vccz .LBB0_985
	s_add_i32 s2, s2, -5
	s_cmp_eq_u32 s2, 0
	s_cselect_b64 s[66:67], -1, 0
	s_nop 0
	s_branch .LBB0_985

.LBB0_1346:
	global_load_dword v130, v153, s[90:91] sc1
	s_mov_b64 s[92:93], -1
	s_waitcnt vmcnt(0)
	v_cmp_lt_u32_e32 vcc, 7, v130
	s_cbranch_vccnz .LBB0_1345
	s_nop 0
	global_load_dword v130, v153, s[90:91] sc1
	s_waitcnt vmcnt(0)
	v_cmp_gt_u32_e32 vcc, 8, v130
	s_cbranch_vccz .LBB0_1345
	s_nop 0
	global_load_dword v130, v153, s[90:91] sc1
	s_waitcnt vmcnt(0)
	v_cmp_gt_u32_e32 vcc, 8, v130
	s_cbranch_vccz .LBB0_1345
	s_nop 0
	global_load_dword v130, v153, s[90:91] sc1
	s_waitcnt vmcnt(0)
	v_cmp_gt_u32_e32 vcc, 8, v130
	s_cbranch_vccz .LBB0_1345
	s_nop 0
	global_load_dword v130, v153, s[90:91] sc1
	s_waitcnt vmcnt(0)
	v_cmp_gt_u32_e32 vcc, 8, v130
	s_cbranch_vccz .LBB0_1345
	s_add_i32 s0, s0, -5
	s_cmp_eq_u32 s0, 0
	s_cselect_b64 s[92:93], -1, 0
	s_nop 0
	s_branch .LBB0_1345

.LBB0_1475:
	global_load_dword v130, v191, s[86:87] sc1
	s_mov_b64 s[88:89], -1
	s_waitcnt vmcnt(0)
	v_cmp_lt_u32_e32 vcc, 7, v130
	s_cbranch_vccnz .LBB0_1474
	s_nop 0
	global_load_dword v130, v191, s[86:87] sc1
	s_waitcnt vmcnt(0)
	v_cmp_gt_u32_e32 vcc, 8, v130
	s_cbranch_vccz .LBB0_1474
	s_nop 0
	global_load_dword v130, v191, s[86:87] sc1
	s_waitcnt vmcnt(0)
	v_cmp_gt_u32_e32 vcc, 8, v130
	s_cbranch_vccz .LBB0_1474
	s_nop 0
	global_load_dword v130, v191, s[86:87] sc1
	s_waitcnt vmcnt(0)
	v_cmp_gt_u32_e32 vcc, 8, v130
	s_cbranch_vccz .LBB0_1474
	s_nop 0
	global_load_dword v130, v191, s[86:87] sc1
	s_waitcnt vmcnt(0)
	v_cmp_gt_u32_e32 vcc, 8, v130
	s_cbranch_vccz .LBB0_1474
	s_add_i32 s7, s7, -5
	s_cmp_eq_u32 s7, 0
	s_cselect_b64 s[88:89], -1, 0
	s_nop 0
	s_branch .LBB0_1474

.LBB0_2138:
	global_load_dword v130, v197, s[62:63] sc1
	s_mov_b64 s[64:65], -1
	s_waitcnt vmcnt(0)
	v_cmp_lt_u32_e32 vcc, 7, v130
	s_cbranch_vccnz .LBB0_2137
	s_nop 0
	global_load_dword v130, v197, s[62:63] sc1
	s_waitcnt vmcnt(0)
	v_cmp_gt_u32_e32 vcc, 8, v130
	s_cbranch_vccz .LBB0_2137
	s_nop 0
	global_load_dword v130, v197, s[62:63] sc1
	s_waitcnt vmcnt(0)
	v_cmp_gt_u32_e32 vcc, 8, v130
	s_cbranch_vccz .LBB0_2137
	s_nop 0
	global_load_dword v130, v197, s[62:63] sc1
	s_waitcnt vmcnt(0)
	v_cmp_gt_u32_e32 vcc, 8, v130
	s_cbranch_vccz .LBB0_2137
	s_nop 0
	global_load_dword v130, v197, s[62:63] sc1
	s_waitcnt vmcnt(0)
	v_cmp_gt_u32_e32 vcc, 8, v130
	s_cbranch_vccz .LBB0_2137
	s_add_i32 s17, s17, -5
	s_cmp_eq_u32 s17, 0
	s_cselect_b64 s[64:65], -1, 0
	s_nop 0
	s_branch .LBB0_2137

.LBB0_2155:
	s_waitcnt lgkmcnt(0)
	global_load_dword v165, v197, s[60:61] sc1
	s_mov_b64 s[62:63], -1
	s_waitcnt vmcnt(0)
	v_readfirstlane_b32 s36, v165
	s_cmp_gt_u32 s36, 31
	s_cbranch_scc1 .LBB0_2154
	s_nop 0
	global_load_dword v165, v197, s[60:61] sc1
	s_waitcnt vmcnt(0)
	v_readfirstlane_b32 s36, v165
	s_cmp_lt_u32 s36, 32
	s_cbranch_scc0 .LBB0_2154
	s_nop 0
	global_load_dword v165, v197, s[60:61] sc1
	s_waitcnt vmcnt(0)
	v_readfirstlane_b32 s36, v165
	s_cmp_lt_u32 s36, 32
	s_cbranch_scc0 .LBB0_2154
	s_nop 0
	global_load_dword v165, v197, s[60:61] sc1
	s_waitcnt vmcnt(0)
	v_readfirstlane_b32 s36, v165
	s_cmp_lt_u32 s36, 32
	s_cbranch_scc0 .LBB0_2154
	s_nop 0
	global_load_dword v165, v197, s[60:61] sc1
	s_waitcnt vmcnt(0)
	v_readfirstlane_b32 s36, v165
	s_cmp_lt_u32 s36, 32
	s_cbranch_scc0 .LBB0_2154
	s_add_i32 s17, s17, -5
	s_cmp_eq_u32 s17, 0
	s_cselect_b64 s[62:63], -1, 0
	s_nop 0
	s_branch .LBB0_2154

.LBB0_2188:
	global_load_dword v4, v197, s[58:59] sc1
	s_mov_b64 s[60:61], -1
	s_waitcnt vmcnt(0)
	v_readfirstlane_b32 s33, v4
	s_cmp_gt_u32 s33, 31
	s_cbranch_scc1 .LBB0_2187
	s_nop 0
	global_load_dword v4, v197, s[58:59] sc1
	s_waitcnt vmcnt(0)
	v_readfirstlane_b32 s33, v4
	s_cmp_lt_u32 s33, 32
	s_cbranch_scc0 .LBB0_2187
	s_nop 0
	global_load_dword v4, v197, s[58:59] sc1
	s_waitcnt vmcnt(0)
	v_readfirstlane_b32 s33, v4
	s_cmp_lt_u32 s33, 32
	s_cbranch_scc0 .LBB0_2187
	s_nop 0
	global_load_dword v4, v197, s[58:59] sc1
	s_waitcnt vmcnt(0)
	v_readfirstlane_b32 s33, v4
	s_cmp_lt_u32 s33, 32
	s_cbranch_scc0 .LBB0_2187
	s_nop 0
	global_load_dword v4, v197, s[58:59] sc1
	s_waitcnt vmcnt(0)
	v_readfirstlane_b32 s33, v4
	s_cmp_lt_u32 s33, 32
	s_cbranch_scc0 .LBB0_2187
	s_add_i32 s17, s17, -5
	s_cmp_eq_u32 s17, 0
	s_cselect_b64 s[60:61], -1, 0
	s_nop 0
	s_branch .LBB0_2187
